# prologue: bias loop 3 iterations of loads in flight per pass; x->bf16 pass warms the next row into L2 behind the current row loads (plus GEMM#1 loop-top vmcnt(0) removed)
# baseline (speedup 1.0000x reference)
; __device__ __forceinline__ void phase_prologue(const KArgs& a, LAS unsigned char* lds, int wave, int lane) {
;     ...
;     if (blockIdx.x < 4) {
;         const int lk = blockIdx.x, l = lk >> 1, kv = lk & 1, j = lane;
;         const float* pe = a.in[kv ? I_PEV : I_PEK] + (size_t)l * 2048; const float* w1 = a.in[kv ? I_W1V : I_W1K] + (size_t)l * 2048 * 64;
;         float s = 0.f;
;         for (int k = wave * 256; k < wave * 256 + 256; ++k) s += pe[k] * w1[(size_t)k * 64 + j];
.Lbias_pass:
	v_lshl_add_u64 v[136:137], v[4:5], 0, s[10:11]
	v_lshl_add_u64 v[138:139], v[136:137], 0, s[10:11]
	s_add_u32 s14, s7, s4
	s_addc_u32 s15, s12, s5
	global_load_dword v40, v[4:5], off offset:-2048
	global_load_dword v41, v[4:5], off offset:-1792
	global_load_dword v42, v[4:5], off offset:-1536
	global_load_dword v43, v[4:5], off offset:-1280
	global_load_dword v44, v[4:5], off offset:-1024
	global_load_dword v45, v[4:5], off offset:-768
	global_load_dword v46, v[4:5], off offset:-512
	global_load_dword v47, v[4:5], off offset:-256
	global_load_dword v48, v[4:5], off
	global_load_dword v49, v[4:5], off offset:256
	global_load_dword v50, v[4:5], off offset:512
	global_load_dword v51, v[4:5], off offset:768
	global_load_dword v52, v[4:5], off offset:1024
	global_load_dword v53, v[4:5], off offset:1280
	global_load_dword v54, v[4:5], off offset:1536
	global_load_dword v55, v[4:5], off offset:1792
	global_load_dwordx4 v[56:59], v15, s[14:15]
	global_load_dwordx4 v[60:63], v15, s[14:15] offset:16
	global_load_dwordx4 v[64:67], v15, s[14:15] offset:32
	global_load_dwordx4 v[68:71], v15, s[14:15] offset:48
	global_load_dword v72, v[136:137], off offset:-2048
	global_load_dword v73, v[136:137], off offset:-1792
	global_load_dword v74, v[136:137], off offset:-1536
	global_load_dword v75, v[136:137], off offset:-1280
	global_load_dword v76, v[136:137], off offset:-1024
	global_load_dword v77, v[136:137], off offset:-768
	global_load_dword v78, v[136:137], off offset:-512
	global_load_dword v79, v[136:137], off offset:-256
	global_load_dword v80, v[136:137], off
	global_load_dword v81, v[136:137], off offset:256
	global_load_dword v82, v[136:137], off offset:512
	global_load_dword v83, v[136:137], off offset:768
	global_load_dword v84, v[136:137], off offset:1024
	global_load_dword v85, v[136:137], off offset:1280
	global_load_dword v86, v[136:137], off offset:1536
	global_load_dword v87, v[136:137], off offset:1792
	global_load_dwordx4 v[88:91], v15, s[14:15] offset:64
	global_load_dwordx4 v[92:95], v15, s[14:15] offset:80
	global_load_dwordx4 v[96:99], v15, s[14:15] offset:96
	global_load_dwordx4 v[100:103], v15, s[14:15] offset:112
	global_load_dword v104, v[138:139], off offset:-2048
	global_load_dword v105, v[138:139], off offset:-1792
	global_load_dword v106, v[138:139], off offset:-1536
	global_load_dword v107, v[138:139], off offset:-1280
	global_load_dword v108, v[138:139], off offset:-1024
	global_load_dword v109, v[138:139], off offset:-768
	global_load_dword v110, v[138:139], off offset:-512
	global_load_dword v111, v[138:139], off offset:-256
	global_load_dword v112, v[138:139], off
	global_load_dword v113, v[138:139], off offset:256
	global_load_dword v114, v[138:139], off offset:512
	global_load_dword v115, v[138:139], off offset:768
	global_load_dword v116, v[138:139], off offset:1024
	global_load_dword v117, v[138:139], off offset:1280
	global_load_dword v118, v[138:139], off offset:1536
	global_load_dword v119, v[138:139], off offset:1792
	global_load_dwordx4 v[120:123], v15, s[14:15] offset:128
	global_load_dwordx4 v[124:127], v15, s[14:15] offset:144
	global_load_dwordx4 v[128:131], v15, s[14:15] offset:160
	global_load_dwordx4 v[132:135], v15, s[14:15] offset:176
	s_add_u32 s4, s4, 0xc0
	s_addc_u32 s5, s5, 0
	v_lshl_add_u64 v[4:5], v[138:139], 0, s[10:11]
	s_waitcnt vmcnt(0)
	v_fmac_f32_e32 v3, v56, v40
	v_fmac_f32_e32 v3, v57, v41
	v_fmac_f32_e32 v3, v58, v42
	v_fmac_f32_e32 v3, v59, v43
	v_fmac_f32_e32 v3, v60, v44
	v_fmac_f32_e32 v3, v61, v45
	v_fmac_f32_e32 v3, v62, v46
	v_fmac_f32_e32 v3, v63, v47
	v_fmac_f32_e32 v3, v64, v48
	v_fmac_f32_e32 v3, v65, v49
	v_fmac_f32_e32 v3, v66, v50
	v_fmac_f32_e32 v3, v67, v51
	v_fmac_f32_e32 v3, v68, v52
	v_fmac_f32_e32 v3, v69, v53
	v_fmac_f32_e32 v3, v70, v54
	v_fmac_f32_e32 v3, v71, v55
	v_fmac_f32_e32 v3, v88, v72
	v_fmac_f32_e32 v3, v89, v73
	v_fmac_f32_e32 v3, v90, v74
	v_fmac_f32_e32 v3, v91, v75
	v_fmac_f32_e32 v3, v92, v76
	v_fmac_f32_e32 v3, v93, v77
	v_fmac_f32_e32 v3, v94, v78
	v_fmac_f32_e32 v3, v95, v79
	v_fmac_f32_e32 v3, v96, v80
	v_fmac_f32_e32 v3, v97, v81
	v_fmac_f32_e32 v3, v98, v82
	v_fmac_f32_e32 v3, v99, v83
	v_fmac_f32_e32 v3, v100, v84
	v_fmac_f32_e32 v3, v101, v85
	v_fmac_f32_e32 v3, v102, v86
	v_fmac_f32_e32 v3, v103, v87
	v_fmac_f32_e32 v3, v120, v104
	v_fmac_f32_e32 v3, v121, v105
	v_fmac_f32_e32 v3, v122, v106
	v_fmac_f32_e32 v3, v123, v107
	v_fmac_f32_e32 v3, v124, v108
	v_fmac_f32_e32 v3, v125, v109
	v_fmac_f32_e32 v3, v126, v110
	v_fmac_f32_e32 v3, v127, v111
	v_fmac_f32_e32 v3, v128, v112
	v_fmac_f32_e32 v3, v129, v113
	v_fmac_f32_e32 v3, v130, v114
	v_fmac_f32_e32 v3, v131, v115
	v_fmac_f32_e32 v3, v132, v116
	v_fmac_f32_e32 v3, v133, v117
	v_fmac_f32_e32 v3, v134, v118
	v_fmac_f32_e32 v3, v135, v119
	s_cmpk_eq_i32 s4, 0x3c0
	s_cbranch_scc0 .Lbias_pass

; __device__ __forceinline__ unsigned pk2(float lo, float hi) { return f2bf(lo) | (f2bf(hi) << 16); }
; __device__ __forceinline__ void phase_xcvt(const float* x, bf16_t* xb, float* ssq, int wave, int lane) {
;     const int gw = blockIdx.x * NWAVES + wave, NGW = gridDim.x * NWAVES;
;     for (int m = gw; m < MTOK; m += NGW) {
;         const f32x4* xr = (const f32x4*)(x + (size_t)m * DM) + lane;
;         f32x4 v[4]; float s = 0.f;
; #pragma unroll
;         for (int j = 0; j < 4; ++j) { v[j] = xr[64 * j]; s += (v[j].x * v[j].x + v[j].y * v[j].y) + (v[j].z * v[j].z + v[j].w * v[j].w); }
;         s = wave_sum(s);
;         u32x2* o8 = (u32x2*)(xb + (size_t)m * DM) + lane;
; #pragma unroll
;         for (int j = 0; j < 4; ++j) { u32x2 w; w.x = pk2(v[j].x, v[j].y); w.y = pk2(v[j].z, v[j].w); o8[64 * j] = w; }
;         if (lane < 16) ssq[(size_t)m * 16 + lane] = (lane == 0) ? s : 0.f;
;     }
.LBB0_103:
	s_waitcnt lgkmcnt(0)
	global_load_dwordx4 v[14:17], v[6:7], off offset:-3072
	global_load_dwordx4 v[18:21], v[6:7], off offset:-2048
	global_load_dwordx4 v[22:25], v[6:7], off offset:-1024
	global_load_dwordx4 v[26:29], v[6:7], off
	s_add_i32 s99, s6, s8
	s_cmp_lt_i32 s99, 0x10000
	s_cselect_b32 s100, s12, 0
	s_cselect_b32 s101, s13, 0
	v_lshl_add_u64 v[60:61], v[6:7], 0, s[100:101]
	global_load_dwordx4 v[62:65], v[60:61], off offset:-3072
	global_load_dwordx4 v[62:65], v[60:61], off offset:-2048
	global_load_dwordx4 v[62:65], v[60:61], off offset:-1024
	global_load_dwordx4 v[62:65], v[60:61], off
	v_lshl_add_u64 v[30:31], s[70:71], 0, v[4:5]
	v_add_co_u32_e64 v30, s[2:3], s14, v30
	s_waitcnt vmcnt(7)
	v_mul_f32_e32 v1, v15, v15
	v_mul_f32_e32 v32, v17, v17
	s_waitcnt vmcnt(6)
	v_mul_f32_e32 v33, v19, v19
	v_mul_f32_e32 v34, v21, v21
	s_waitcnt vmcnt(5)
	v_mul_f32_e32 v35, v23, v23
	v_mul_f32_e32 v36, v25, v25
	v_fmac_f32_e32 v1, v14, v14
	v_fmac_f32_e32 v32, v16, v16
	v_fmac_f32_e32 v33, v18, v18
	v_fmac_f32_e32 v34, v20, v20
	s_waitcnt vmcnt(4)
	v_mul_f32_e32 v37, v27, v27
	v_mul_f32_e32 v38, v29, v29
	v_fmac_f32_e32 v35, v22, v22
	v_fmac_f32_e32 v36, v24, v24
	v_add_f32_e32 v1, v1, v32
	v_add_f32_e32 v32, v33, v34
	v_fmac_f32_e32 v37, v26, v26
	v_fmac_f32_e32 v38, v28, v28
	v_add_f32_e32 v33, v35, v36
	v_add_f32_e32 v1, v1, v32
	v_add_f32_e32 v34, v37, v38
	v_add_f32_e32 v1, v1, v33
	v_add_f32_e32 v1, v1, v34
	ds_bpermute_b32 v32, v8, v1
	v_bfe_u32 v39, v14, 16, 1
	v_bfe_u32 v41, v16, 16, 1
	v_bfe_u32 v45, v20, 16, 1
	v_bfe_u32 v40, v15, 16, 1
	s_waitcnt lgkmcnt(0)
	v_add_f32_e32 v1, v1, v32
	ds_bpermute_b32 v32, v9, v1
	v_bfe_u32 v42, v17, 16, 1
	v_bfe_u32 v46, v21, 16, 1
	v_add3_u32 v14, v14, v39, s7
	v_add3_u32 v16, v16, v41, s7
	s_waitcnt lgkmcnt(0)
	v_add_f32_e32 v1, v1, v32
	ds_bpermute_b32 v32, v10, v1
	v_add3_u32 v20, v20, v45, s7
	v_add3_u32 v15, v15, v40, s7
	v_add3_u32 v17, v17, v42, s7
	v_add3_u32 v21, v21, v46, s7
	s_waitcnt lgkmcnt(0)
	v_add_f32_e32 v1, v1, v32
	ds_bpermute_b32 v32, v11, v1
	v_lshrrev_b32_e32 v14, 16, v14
	v_lshrrev_b32_e32 v16, 16, v16
	v_lshrrev_b32_e32 v20, 16, v20
	v_and_or_b32 v14, v15, s9, v14
	s_waitcnt lgkmcnt(0)
	v_add_f32_e32 v1, v1, v32
	v_and_or_b32 v15, v17, s9, v16
	v_and_or_b32 v17, v21, s9, v20
	ds_bpermute_b32 v21, v12, v1
	v_bfe_u32 v43, v18, 16, 1
	v_bfe_u32 v47, v22, 16, 1
	v_bfe_u32 v49, v24, 16, 1
	v_bfe_u32 v44, v19, 16, 1
	v_bfe_u32 v48, v23, 16, 1
	v_bfe_u32 v50, v25, 16, 1
	v_add3_u32 v18, v18, v43, s7
	v_add3_u32 v22, v22, v47, s7
	v_add3_u32 v24, v24, v49, s7
	v_addc_co_u32_e64 v31, s[2:3], 0, v31, s[2:3]
	v_add3_u32 v19, v19, v44, s7
	v_add3_u32 v23, v23, v48, s7
	v_add3_u32 v25, v25, v50, s7
	v_lshrrev_b32_e32 v18, 16, v18
	v_lshrrev_b32_e32 v22, 16, v22
	v_lshrrev_b32_e32 v24, 16, v24
	s_waitcnt lgkmcnt(0)
	v_add_f32_e32 v1, v1, v21
	v_and_or_b32 v16, v19, s9, v18
	v_and_or_b32 v18, v23, s9, v22
	v_and_or_b32 v19, v25, s9, v24
	global_store_dwordx2 v[30:31], v[14:15], off
	global_store_dwordx2 v[30:31], v[16:17], off offset:512
	global_store_dwordx2 v[30:31], v[18:19], off offset:1024
	ds_bpermute_b32 v14, v13, v1
	v_bfe_u32 v51, v26, 16, 1
	v_bfe_u32 v53, v28, 16, 1
	v_bfe_u32 v52, v27, 16, 1
	v_add3_u32 v26, v26, v51, s7
	v_add3_u32 v28, v28, v53, s7
	v_bfe_u32 v16, v29, 16, 1
	v_add3_u32 v27, v27, v52, s7
	v_lshrrev_b32_e32 v26, 16, v26
	v_lshrrev_b32_e32 v15, 16, v28
	v_add3_u32 v16, v29, v16, s7
	v_and_or_b32 v20, v27, s9, v26
	v_and_or_b32 v21, v16, s9, v15
	global_store_dwordx2 v[30:31], v[20:21], off offset:1536
	s_and_saveexec_b64 s[2:3], vcc
	s_cbranch_execz .LBB0_102
	s_waitcnt lgkmcnt(0)
	v_add_f32_e32 v1, v1, v14
	v_cndmask_b32_e64 v1, 0, v1, s[0:1]
	v_lshl_add_u64 v[14:15], s[70:71], 0, v[2:3]
	global_store_dword v[14:15], v1, off
	s_branch .LBB0_102
